# P0 xp f32->bf16 copy loop software-pipelined (2 groups in flight) with nt loads/stores; nt on LN1/LN2 streaming row loads and output stores
# speedup vs baseline: 1.0251x; 1.0063x over previous
.LBB0_100:
	s_load_dwordx16 s[8:23], s[0:1], 0x0
	v_writelane_b32 v251, s34, 19
	s_add_u32 s96, s90, 0x1840800
	s_addc_u32 s97, s91, 0
	s_ashr_i32 s7, s6, 31
	s_waitcnt lgkmcnt(0)
	v_writelane_b32 v251, s8, 3
	v_mov_b64_e32 v[2:3], 0x3ffffff
	s_ashr_i32 s95, s94, 31
	v_writelane_b32 v251, s9, 4
	v_writelane_b32 v251, s10, 5
	v_writelane_b32 v251, s11, 6
	v_writelane_b32 v251, s12, 7
	v_writelane_b32 v251, s13, 8
	v_writelane_b32 v251, s14, 9
	v_writelane_b32 v251, s15, 10
	v_writelane_b32 v251, s16, 11
	v_writelane_b32 v251, s17, 12
	v_writelane_b32 v251, s18, 13
	v_writelane_b32 v251, s19, 14
	v_writelane_b32 v251, s20, 15
	v_writelane_b32 v251, s21, 16
	v_writelane_b32 v251, s22, 17
	v_writelane_b32 v251, s23, 18
	s_lshl_b64 s[10:11], s[6:7], 9
	v_cmp_gt_u64_e32 vcc, s[10:11], v[2:3]
	s_lshl_b64 s[8:9], s[94:95], 9
	v_mov_b32_e32 v31, 0
	v_or_b32_e32 v28, s10, v30
	v_mov_b32_e32 v29, s11
	s_mov_b64 s[4:5], 0x3ffffff
	s_and_b64 vcc, exec, vcc
	s_mul_hi_i32 s13, s94, 0x600
	s_mul_i32 s12, s94, 0x600
	s_mul_hi_i32 s28, s94, 0xc00
	s_mul_i32 s29, s94, 0xc00
	s_cbranch_vccnz .LBB0_110
	s_lshl_b64 s[0:1], s[6:7], 11
	v_readlane_b32 s52, v251, 3
	v_readlane_b32 s53, v251, 4
	s_add_u32 s0, s52, s0
	v_lshlrev_b32_e32 v2, 5, v26
	v_mov_b32_e32 v3, v31
	s_addc_u32 s1, s53, s1
	v_lshl_add_u64 v[2:3], s[0:1], 0, v[2:3]
	s_lshl_b64 s[14:15], s[94:95], 13
	s_lshl_b64 s[16:17], s[94:95], 10
	s_lshl_b64 s[0:1], s[6:7], 10
	s_add_u32 s2, s16, s0
	v_lshl_add_u64 v[32:33], v[2:3], 0, 16
	s_addc_u32 s3, s17, s1
	v_lshlrev_b32_e32 v2, 4, v26
	v_or_b32_e32 v34, s2, v2
	v_mov_b32_e32 v35, s3
	s_lshl_b64 s[18:19], s[94:95], 12
	s_lshl_b64 s[2:3], s[94:95], 11
	s_add_u32 s2, s2, s0
	s_addc_u32 s3, s3, s1
	v_or_b32_e32 v36, s0, v2
	s_add_u32 s0, s29, s0
	v_mov_b32_e32 v37, s1
	s_addc_u32 s1, s28, s1
	v_or_b32_e32 v38, s2, v2
	v_mov_b32_e32 v39, s3
	v_or_b32_e32 v40, s0, v2
	v_mov_b32_e32 v41, s1
	s_mov_b64 s[20:21], 0
	s_mov_b64 s[22:23], 0x4000000
	s_mov_b64 s[24:25], s[96:97]
	v_mov_b64_e32 v[2:3], v[28:29]
	v_readlane_b32 s54, v251, 5
	v_readlane_b32 s55, v251, 6
	v_readlane_b32 s56, v251, 7
	v_readlane_b32 s57, v251, 8
	v_readlane_b32 s58, v251, 9
	v_readlane_b32 s59, v251, 10
	v_readlane_b32 s60, v251, 11
	v_readlane_b32 s61, v251, 12
	v_readlane_b32 s62, v251, 13
	v_readlane_b32 s63, v251, 14
	v_readlane_b32 s64, v251, 15
	v_readlane_b32 s65, v251, 16
	v_readlane_b32 s66, v251, 17
	v_readlane_b32 s67, v251, 18
	v_lshlrev_b32_e32 v2, 2, v28
	v_lshlrev_b32_e32 v3, 1, v28
	s_mov_b64 s[0:1], s[52:53]
	s_mov_b64 s[2:3], s[96:97]
	global_load_dwordx4 v[68:71], v2, s[0:1] nt
	global_load_dwordx4 v[72:75], v2, s[0:1] offset:16 nt
	s_add_u32 s0, s0, 0x400000
	s_addc_u32 s1, s1, 0
	global_load_dwordx4 v[76:79], v2, s[0:1] nt
	global_load_dwordx4 v[80:83], v2, s[0:1] offset:16 nt
	s_add_u32 s0, s0, 0x400000
	s_addc_u32 s1, s1, 0
	global_load_dwordx4 v[84:87], v2, s[0:1] nt
	global_load_dwordx4 v[88:91], v2, s[0:1] offset:16 nt
	s_add_u32 s0, s0, 0x400000
	s_addc_u32 s1, s1, 0
	global_load_dwordx4 v[92:95], v2, s[0:1] nt
	global_load_dwordx4 v[96:99], v2, s[0:1] offset:16 nt
	s_add_u32 s0, s0, 0x400000
	s_addc_u32 s1, s1, 0
	global_load_dwordx4 v[100:103], v2, s[0:1] nt
	global_load_dwordx4 v[104:107], v2, s[0:1] offset:16 nt
	s_add_u32 s0, s0, 0x400000
	s_addc_u32 s1, s1, 0
	global_load_dwordx4 v[108:111], v2, s[0:1] nt
	global_load_dwordx4 v[112:115], v2, s[0:1] offset:16 nt
	s_add_u32 s0, s0, 0x400000
	s_addc_u32 s1, s1, 0
	global_load_dwordx4 v[116:119], v2, s[0:1] nt
	global_load_dwordx4 v[120:123], v2, s[0:1] offset:16 nt
	s_add_u32 s0, s0, 0x400000
	s_addc_u32 s1, s1, 0
	global_load_dwordx4 v[124:127], v2, s[0:1] nt
	global_load_dwordx4 v[128:131], v2, s[0:1] offset:16 nt
	s_add_u32 s0, s0, 0x400000
	s_addc_u32 s1, s1, 0
	s_mov_b32 s14, 0
	s_waitcnt vmcnt(8)
.Lxp_loop:
	s_waitcnt vmcnt(12)
	v_cvt_pk_bf16_f32 v68, v68, v69
	v_cvt_pk_bf16_f32 v69, v70, v71
	v_cvt_pk_bf16_f32 v70, v72, v73
	v_cvt_pk_bf16_f32 v71, v74, v75
	global_store_dwordx4 v3, v[68:71], s[2:3] nt
	s_add_u32 s2, s2, 0x200000
	s_addc_u32 s3, s3, 0
	v_cvt_pk_bf16_f32 v76, v76, v77
	v_cvt_pk_bf16_f32 v77, v78, v79
	v_cvt_pk_bf16_f32 v78, v80, v81
	v_cvt_pk_bf16_f32 v79, v82, v83
	global_store_dwordx4 v3, v[76:79], s[2:3] nt
	s_add_u32 s2, s2, 0x200000
	s_addc_u32 s3, s3, 0
	v_cvt_pk_bf16_f32 v84, v84, v85
	v_cvt_pk_bf16_f32 v85, v86, v87
	v_cvt_pk_bf16_f32 v86, v88, v89
	v_cvt_pk_bf16_f32 v87, v90, v91
	global_store_dwordx4 v3, v[84:87], s[2:3] nt
	s_add_u32 s2, s2, 0x200000
	s_addc_u32 s3, s3, 0
	v_cvt_pk_bf16_f32 v92, v92, v93
	v_cvt_pk_bf16_f32 v93, v94, v95
	v_cvt_pk_bf16_f32 v94, v96, v97
	v_cvt_pk_bf16_f32 v95, v98, v99
	global_store_dwordx4 v3, v[92:95], s[2:3] nt
	s_add_u32 s2, s2, 0x200000
	s_addc_u32 s3, s3, 0
	s_cmp_eq_u32 s14, 7
	s_cbranch_scc1 .Lxp_last
	global_load_dwordx4 v[68:71], v2, s[0:1] nt
	global_load_dwordx4 v[72:75], v2, s[0:1] offset:16 nt
	s_add_u32 s0, s0, 0x400000
	s_addc_u32 s1, s1, 0
	global_load_dwordx4 v[76:79], v2, s[0:1] nt
	global_load_dwordx4 v[80:83], v2, s[0:1] offset:16 nt
	s_add_u32 s0, s0, 0x400000
	s_addc_u32 s1, s1, 0
	global_load_dwordx4 v[84:87], v2, s[0:1] nt
	global_load_dwordx4 v[88:91], v2, s[0:1] offset:16 nt
	s_add_u32 s0, s0, 0x400000
	s_addc_u32 s1, s1, 0
	global_load_dwordx4 v[92:95], v2, s[0:1] nt
	global_load_dwordx4 v[96:99], v2, s[0:1] offset:16 nt
	s_add_u32 s0, s0, 0x400000
	s_addc_u32 s1, s1, 0
	s_waitcnt vmcnt(12)
	v_cvt_pk_bf16_f32 v100, v100, v101
	v_cvt_pk_bf16_f32 v101, v102, v103
	v_cvt_pk_bf16_f32 v102, v104, v105
	v_cvt_pk_bf16_f32 v103, v106, v107
	global_store_dwordx4 v3, v[100:103], s[2:3] nt
	s_add_u32 s2, s2, 0x200000
	s_addc_u32 s3, s3, 0
	v_cvt_pk_bf16_f32 v108, v108, v109
	v_cvt_pk_bf16_f32 v109, v110, v111
	v_cvt_pk_bf16_f32 v110, v112, v113
	v_cvt_pk_bf16_f32 v111, v114, v115
	global_store_dwordx4 v3, v[108:111], s[2:3] nt
	s_add_u32 s2, s2, 0x200000
	s_addc_u32 s3, s3, 0
	v_cvt_pk_bf16_f32 v116, v116, v117
	v_cvt_pk_bf16_f32 v117, v118, v119
	v_cvt_pk_bf16_f32 v118, v120, v121
	v_cvt_pk_bf16_f32 v119, v122, v123
	global_store_dwordx4 v3, v[116:119], s[2:3] nt
	s_add_u32 s2, s2, 0x200000
	s_addc_u32 s3, s3, 0
	v_cvt_pk_bf16_f32 v124, v124, v125
	v_cvt_pk_bf16_f32 v125, v126, v127
	v_cvt_pk_bf16_f32 v126, v128, v129
	v_cvt_pk_bf16_f32 v127, v130, v131
	global_store_dwordx4 v3, v[124:127], s[2:3] nt
	s_add_u32 s2, s2, 0x200000
	s_addc_u32 s3, s3, 0
	global_load_dwordx4 v[100:103], v2, s[0:1] nt
	global_load_dwordx4 v[104:107], v2, s[0:1] offset:16 nt
	s_add_u32 s0, s0, 0x400000
	s_addc_u32 s1, s1, 0
	global_load_dwordx4 v[108:111], v2, s[0:1] nt
	global_load_dwordx4 v[112:115], v2, s[0:1] offset:16 nt
	s_add_u32 s0, s0, 0x400000
	s_addc_u32 s1, s1, 0
	global_load_dwordx4 v[116:119], v2, s[0:1] nt
	global_load_dwordx4 v[120:123], v2, s[0:1] offset:16 nt
	s_add_u32 s0, s0, 0x400000
	s_addc_u32 s1, s1, 0
	global_load_dwordx4 v[124:127], v2, s[0:1] nt
	global_load_dwordx4 v[128:131], v2, s[0:1] offset:16 nt
	s_add_u32 s0, s0, 0x400000
	s_addc_u32 s1, s1, 0
	s_add_i32 s14, s14, 1
	s_branch .Lxp_loop
.Lxp_last:
	s_waitcnt vmcnt(4)
	v_cvt_pk_bf16_f32 v100, v100, v101
	v_cvt_pk_bf16_f32 v101, v102, v103
	v_cvt_pk_bf16_f32 v102, v104, v105
	v_cvt_pk_bf16_f32 v103, v106, v107
	global_store_dwordx4 v3, v[100:103], s[2:3] nt
	s_add_u32 s2, s2, 0x200000
	s_addc_u32 s3, s3, 0
	v_cvt_pk_bf16_f32 v108, v108, v109
	v_cvt_pk_bf16_f32 v109, v110, v111
	v_cvt_pk_bf16_f32 v110, v112, v113
	v_cvt_pk_bf16_f32 v111, v114, v115
	global_store_dwordx4 v3, v[108:111], s[2:3] nt
	s_add_u32 s2, s2, 0x200000
	s_addc_u32 s3, s3, 0
	v_cvt_pk_bf16_f32 v116, v116, v117
	v_cvt_pk_bf16_f32 v117, v118, v119
	v_cvt_pk_bf16_f32 v118, v120, v121
	v_cvt_pk_bf16_f32 v119, v122, v123
	global_store_dwordx4 v3, v[116:119], s[2:3] nt
	s_add_u32 s2, s2, 0x200000
	s_addc_u32 s3, s3, 0
	v_cvt_pk_bf16_f32 v124, v124, v125
	v_cvt_pk_bf16_f32 v125, v126, v127
	v_cvt_pk_bf16_f32 v126, v128, v129
	v_cvt_pk_bf16_f32 v127, v130, v131
	global_store_dwordx4 v3, v[124:127], s[2:3] nt
	s_add_u32 s2, s2, 0x200000
	s_addc_u32 s3, s3, 0
	s_branch .LBB0_110

.LBB0_1741:
	s_or_b64 exec, exec, s[8:9]
	global_load_dwordx4 v[20:23], v[38:39], off
	global_load_dwordx4 v[24:27], v[40:41], off
	v_sub_f32_e32 v13, v13, v16
	v_sub_f32_e32 v12, v12, v16
	s_lshl_b64 s[8:9], s[14:15], 11
	v_sub_f32_e32 v15, v15, v16
	v_sub_f32_e32 v14, v14, v16
	v_pk_mul_f32 v[12:13], v[12:13], v[18:19] op_sel_hi:[1,0]
	v_pk_mul_f32 v[14:15], v[14:15], v[18:19] op_sel_hi:[1,0]
	v_lshl_add_u64 v[28:29], v[42:43], 0, s[8:9]
	v_sub_f32_e32 v9, v9, v16
	v_sub_f32_e32 v8, v8, v16
	v_sub_f32_e32 v11, v11, v16
	v_sub_f32_e32 v10, v10, v16
	v_pk_mul_f32 v[8:9], v[8:9], v[18:19] op_sel_hi:[1,0]
	v_pk_mul_f32 v[10:11], v[10:11], v[18:19] op_sel_hi:[1,0]
	v_sub_f32_e32 v5, v5, v16
	v_sub_f32_e32 v4, v4, v16
	v_sub_f32_e32 v7, v7, v16
	v_sub_f32_e32 v6, v6, v16
	v_pk_mul_f32 v[4:5], v[4:5], v[18:19] op_sel_hi:[1,0]
	v_pk_mul_f32 v[6:7], v[6:7], v[18:19] op_sel_hi:[1,0]
	v_sub_f32_e32 v1, v1, v16
	v_sub_f32_e32 v0, v0, v16
	v_sub_f32_e32 v3, v3, v16
	v_sub_f32_e32 v2, v2, v16
	v_pk_mul_f32 v[0:1], v[0:1], v[18:19] op_sel_hi:[1,0]
	v_pk_mul_f32 v[2:3], v[2:3], v[18:19] op_sel_hi:[1,0]
	s_waitcnt vmcnt(0)
	v_pk_fma_f32 v[12:13], v[12:13], v[20:21], v[24:25]
	v_pk_fma_f32 v[14:15], v[14:15], v[22:23], v[26:27]
	v_cvt_pk_bf16_f32 v12, v12, v13
	s_nop 0
	v_cvt_pk_bf16_f32 v13, v14, v15
	global_store_dwordx2 v[28:29], v[12:13], off nt
	global_load_dwordx4 v[12:15], v[38:39], off offset:1024
	s_nop 0
	global_load_dwordx4 v[20:23], v[40:41], off offset:1024
	s_waitcnt vmcnt(0)
	v_pk_fma_f32 v[8:9], v[8:9], v[12:13], v[20:21]
	v_pk_fma_f32 v[10:11], v[10:11], v[14:15], v[22:23]
	v_cvt_pk_bf16_f32 v8, v8, v9
	s_nop 0
	v_cvt_pk_bf16_f32 v9, v10, v11
	global_store_dwordx2 v[28:29], v[8:9], off offset:512 nt
	global_load_dwordx4 v[8:11], v[38:39], off offset:2048
	s_nop 0
	global_load_dwordx4 v[12:15], v[40:41], off offset:2048
	s_waitcnt vmcnt(0)
	v_pk_fma_f32 v[4:5], v[4:5], v[8:9], v[12:13]
	v_pk_fma_f32 v[6:7], v[6:7], v[10:11], v[14:15]
	v_cvt_pk_bf16_f32 v4, v4, v5
	s_nop 0
	v_cvt_pk_bf16_f32 v5, v6, v7
	global_store_dwordx2 v[28:29], v[4:5], off offset:1024 nt
	global_load_dwordx4 v[4:7], v[38:39], off offset:3072
	s_nop 0
	global_load_dwordx4 v[8:11], v[40:41], off offset:3072
	s_waitcnt vmcnt(0)
	v_pk_fma_f32 v[0:1], v[0:1], v[4:5], v[8:9]
	v_pk_fma_f32 v[2:3], v[2:3], v[6:7], v[10:11]
	v_cvt_pk_bf16_f32 v0, v0, v1
	s_nop 0
	v_cvt_pk_bf16_f32 v1, v2, v3
	global_store_dwordx2 v[28:29], v[0:1], off offset:1536 nt

.LBB0_1745:
	s_or_b64 exec, exec, s[8:9]
	s_lshl_b64 s[8:9], s[20:21], 12
	v_lshl_add_u64 v[0:1], v[34:35], 0, s[8:9]
	global_load_dwordx4 v[28:31], v[0:1], off nt
	global_load_dwordx4 v[24:27], v[0:1], off offset:1024 nt
	global_load_dwordx4 v[20:23], v[0:1], off offset:2048 nt
	global_load_dwordx4 v[16:19], v[0:1], off offset:3072 nt
	s_add_i32 s14, s20, s76
	s_cmp_lt_i32 s14, 0x10100
	s_cselect_b64 s[18:19], -1, 0
	s_and_b64 s[8:9], s[18:19], exec
	s_cselect_b32 s8, s14, s20
	v_mov_b32_e32 v45, v32
	v_mov_b32_e32 v33, v32
	s_ashr_i32 s9, s8, 31
	s_and_saveexec_b64 s[22:23], s[4:5]
	s_cbranch_execz .LBB0_1747
	s_lshl_b64 s[26:27], s[8:9], 7
	v_lshl_add_u64 v[0:1], v[36:37], 0, s[26:27]
	global_load_dwordx2 v[0:1], v[0:1], off
	s_waitcnt vmcnt(0)
	v_mov_b32_e32 v45, v0
	v_mov_b32_e32 v33, v1
.LBB0_1747:
	s_or_b64 exec, exec, s[22:23]
	s_lshl_b64 s[8:9], s[8:9], 12
	v_lshl_add_u64 v[50:51], v[34:35], 0, s[8:9]
	global_load_dwordx4 v[12:15], v[50:51], off nt
	global_load_dwordx4 v[8:11], v[50:51], off offset:1024 nt
	global_load_dwordx4 v[4:7], v[50:51], off offset:2048 nt
	global_load_dwordx4 v[0:3], v[50:51], off offset:3072 nt
	v_mov_b32_e32 v47, v46
	s_nop 1
	v_mov_b32_dpp v47, v47 quad_perm:[1,0,3,2] row_mask:0xf bank_mask:0xf
	v_add_f32_e32 v46, v46, v47
	v_mov_b32_e32 v47, v46
	s_nop 1
	v_mov_b32_dpp v47, v47 quad_perm:[2,3,0,1] row_mask:0xf bank_mask:0xf
	v_add_f32_e32 v46, v46, v47
	v_mov_b32_e32 v47, v46
	s_nop 1
	v_mov_b32_dpp v47, v47 row_ror:4 row_mask:0xf bank_mask:0xf
	v_add_f32_e32 v46, v46, v47
	v_mov_b32_e32 v47, v46
	s_nop 1
	v_mov_b32_dpp v47, v47 row_ror:8 row_mask:0xf bank_mask:0xf
	v_add_f32_e32 v46, v46, v47
	v_mov_b32_e32 v47, v44
	v_readfirstlane_b32 s8, v46
	s_nop 0
	v_mov_b32_dpp v47, v47 quad_perm:[1,0,3,2] row_mask:0xf bank_mask:0xf
	v_add_f32_e32 v44, v44, v47
	v_mov_b32_e32 v47, v44
	v_cvt_i32_f32_e32 v46, s8
	v_cvt_f32_i32_e32 v46, v46
	v_mov_b32_dpp v47, v47 quad_perm:[2,3,0,1] row_mask:0xf bank_mask:0xf
	v_add_f32_e32 v44, v44, v47
	v_mov_b32_e32 v47, v44
	v_mul_f32_e32 v46, 0x3a800000, v46
	s_nop 0
	v_mov_b32_dpp v47, v47 row_ror:4 row_mask:0xf bank_mask:0xf
	v_add_f32_e32 v44, v44, v47
	v_mov_b32_e32 v47, v44
	s_nop 1
	v_mov_b32_dpp v47, v47 row_ror:8 row_mask:0xf bank_mask:0xf
	v_add_f32_e32 v44, v44, v47
	v_mul_f32_e32 v47, v46, v46
	v_readfirstlane_b32 s8, v44
	s_nop 1
	v_cvt_i32_f32_e32 v44, s8
	v_cvt_f32_i32_e32 v44, v44
	v_fma_f32 v44, v44, s24, -v47
	v_max_f32_e32 v44, 0, v44
	v_add_f32_e32 v44, 0x3727c5ac, v44
	v_mul_f32_e32 v47, 0x4f800000, v44
	v_cmp_gt_f32_e32 vcc, s25, v44
	s_nop 1
	v_cndmask_b32_e32 v44, v44, v47, vcc
	v_sqrt_f32_e32 v47, v44
	s_nop 0
	v_add_u32_e32 v49, -1, v47
	v_fma_f32 v50, -v49, v47, v44
	v_cmp_ge_f32_e64 s[8:9], 0, v50
	v_add_u32_e32 v50, 1, v47
	s_nop 0
	v_cndmask_b32_e64 v49, v47, v49, s[8:9]
	v_fma_f32 v47, -v50, v47, v44
	v_cmp_lt_f32_e64 s[8:9], 0, v47
	s_nop 1
	v_cndmask_b32_e64 v47, v49, v50, s[8:9]
	v_mul_f32_e32 v49, 0x37800000, v47
	v_cndmask_b32_e32 v47, v47, v49, vcc
	v_cmp_class_f32_e32 vcc, v44, v48
	s_nop 1
	v_cndmask_b32_e32 v44, v47, v44, vcc
	v_div_scale_f32 v47, s[8:9], v44, v44, 1.0
	v_rcp_f32_e32 v49, v47
	s_nop 0
	v_fma_f32 v50, -v47, v49, 1.0
	v_fmac_f32_e32 v49, v50, v49
	v_div_scale_f32 v50, vcc, 1.0, v44, 1.0
	v_mul_f32_e32 v51, v50, v49
	v_fma_f32 v52, -v47, v51, v50
	v_fmac_f32_e32 v51, v52, v49
	v_fma_f32 v47, -v47, v51, v50
	v_div_fmas_f32 v47, v47, v49, v51
	v_div_fixup_f32 v44, v47, v44, 1.0
	s_and_saveexec_b64 s[8:9], s[6:7]
	s_cbranch_execz .LBB0_1749
	s_lshl_b64 s[22:23], s[20:21], 3
	s_add_u32 s22, s12, s22
	s_addc_u32 s23, s13, s23
	v_mov_b32_e32 v47, v44
	global_store_dwordx2 v32, v[46:47], s[22:23]
.LBB0_1749:
	s_or_b64 exec, exec, s[8:9]
	global_load_dwordx4 v[50:53], v[38:39], off
	global_load_dwordx4 v[54:57], v[40:41], off
	s_waitcnt vmcnt(9)
	v_sub_f32_e32 v29, v29, v46
	v_sub_f32_e32 v28, v28, v46
	s_lshl_b64 s[8:9], s[20:21], 11
	v_sub_f32_e32 v31, v31, v46
	v_sub_f32_e32 v30, v30, v46
	v_pk_mul_f32 v[28:29], v[28:29], v[44:45] op_sel_hi:[1,0]
	v_pk_mul_f32 v[30:31], v[30:31], v[44:45] op_sel_hi:[1,0]
	v_lshl_add_u64 v[58:59], v[42:43], 0, s[8:9]
	s_waitcnt vmcnt(8)
	v_sub_f32_e32 v25, v25, v46
	v_sub_f32_e32 v24, v24, v46
	v_sub_f32_e32 v27, v27, v46
	v_sub_f32_e32 v26, v26, v46
	v_pk_mul_f32 v[24:25], v[24:25], v[44:45] op_sel_hi:[1,0]
	v_pk_mul_f32 v[26:27], v[26:27], v[44:45] op_sel_hi:[1,0]
	s_waitcnt vmcnt(7)
	v_sub_f32_e32 v21, v21, v46
	v_sub_f32_e32 v20, v20, v46
	v_sub_f32_e32 v23, v23, v46
	v_sub_f32_e32 v22, v22, v46
	v_pk_mul_f32 v[20:21], v[20:21], v[44:45] op_sel_hi:[1,0]
	v_pk_mul_f32 v[22:23], v[22:23], v[44:45] op_sel_hi:[1,0]
	s_waitcnt vmcnt(6)
	v_sub_f32_e32 v17, v17, v46
	v_sub_f32_e32 v16, v16, v46
	v_sub_f32_e32 v19, v19, v46
	v_sub_f32_e32 v18, v18, v46
	v_pk_mul_f32 v[16:17], v[16:17], v[44:45] op_sel_hi:[1,0]
	v_pk_mul_f32 v[18:19], v[18:19], v[44:45] op_sel_hi:[1,0]
	s_andn2_b64 vcc, exec, s[18:19]
	s_waitcnt vmcnt(0)
	v_pk_fma_f32 v[28:29], v[28:29], v[50:51], v[54:55]
	v_pk_fma_f32 v[30:31], v[30:31], v[52:53], v[56:57]
	v_cvt_pk_bf16_f32 v28, v28, v29
	s_nop 0
	v_cvt_pk_bf16_f32 v29, v30, v31
	global_store_dwordx2 v[58:59], v[28:29], off nt
	global_load_dwordx4 v[28:31], v[38:39], off offset:1024
	s_nop 0
	global_load_dwordx4 v[50:53], v[40:41], off offset:1024
	s_waitcnt vmcnt(0)
	v_pk_fma_f32 v[24:25], v[24:25], v[28:29], v[50:51]
	v_pk_fma_f32 v[26:27], v[26:27], v[30:31], v[52:53]
	v_cvt_pk_bf16_f32 v24, v24, v25
	s_nop 0
	v_cvt_pk_bf16_f32 v25, v26, v27
	global_store_dwordx2 v[58:59], v[24:25], off offset:512 nt
	global_load_dwordx4 v[24:27], v[38:39], off offset:2048
	s_nop 0
	global_load_dwordx4 v[28:31], v[40:41], off offset:2048
	s_waitcnt vmcnt(0)
	v_pk_fma_f32 v[20:21], v[20:21], v[24:25], v[28:29]
	v_pk_fma_f32 v[22:23], v[22:23], v[26:27], v[30:31]
	v_cvt_pk_bf16_f32 v20, v20, v21
	s_nop 0
	v_cvt_pk_bf16_f32 v21, v22, v23
	global_store_dwordx2 v[58:59], v[20:21], off offset:1024 nt
	global_load_dwordx4 v[20:23], v[38:39], off offset:3072
	s_nop 0
	global_load_dwordx4 v[24:27], v[40:41], off offset:3072
	s_waitcnt vmcnt(0)
	v_pk_fma_f32 v[16:17], v[16:17], v[20:21], v[24:25]
	v_pk_fma_f32 v[18:19], v[18:19], v[22:23], v[26:27]
	v_cvt_pk_bf16_f32 v16, v16, v17
	s_nop 0
	v_cvt_pk_bf16_f32 v17, v18, v19
	global_store_dwordx2 v[58:59], v[16:17], off offset:1536 nt
	s_cbranch_vccnz .LBB0_1742
	v_mov_b32_e32 v16, v45
	s_ashr_i32 s15, s14, 31
	s_nop 0
	v_mov_b32_dpp v16, v16 quad_perm:[1,0,3,2] row_mask:0xf bank_mask:0xf
	v_add_f32_e32 v16, v45, v16
	v_mov_b32_e32 v17, v16
	s_nop 1
	v_mov_b32_dpp v17, v17 quad_perm:[2,3,0,1] row_mask:0xf bank_mask:0xf
	v_add_f32_e32 v16, v16, v17
	v_mov_b32_e32 v17, v16
	s_nop 1
	v_mov_b32_dpp v17, v17 row_ror:4 row_mask:0xf bank_mask:0xf
	v_add_f32_e32 v16, v16, v17
	v_mov_b32_e32 v17, v16
	s_nop 1
	v_mov_b32_dpp v17, v17 row_ror:8 row_mask:0xf bank_mask:0xf
	v_add_f32_e32 v16, v16, v17
	v_mov_b32_e32 v17, v33
	v_readfirstlane_b32 s8, v16
	s_nop 0
	v_mov_b32_dpp v17, v17 quad_perm:[1,0,3,2] row_mask:0xf bank_mask:0xf
	v_add_f32_e32 v17, v33, v17
	v_mov_b32_e32 v18, v17
	v_cvt_i32_f32_e32 v16, s8
	v_cvt_f32_i32_e32 v16, v16
	v_mov_b32_dpp v18, v18 quad_perm:[2,3,0,1] row_mask:0xf bank_mask:0xf
	v_add_f32_e32 v17, v17, v18
	v_mov_b32_e32 v18, v17
	v_mul_f32_e32 v16, 0x3a800000, v16
	s_nop 0
	v_mov_b32_dpp v18, v18 row_ror:4 row_mask:0xf bank_mask:0xf
	v_add_f32_e32 v17, v17, v18
	v_mov_b32_e32 v18, v17
	s_nop 1
	v_mov_b32_dpp v18, v18 row_ror:8 row_mask:0xf bank_mask:0xf
	v_add_f32_e32 v17, v17, v18
	v_mul_f32_e32 v18, v16, v16
	v_readfirstlane_b32 s8, v17
	s_nop 1
	v_cvt_i32_f32_e32 v17, s8
	v_cvt_f32_i32_e32 v17, v17
	v_fma_f32 v17, v17, s24, -v18
	v_max_f32_e32 v17, 0, v17
	v_add_f32_e32 v17, 0x3727c5ac, v17
	v_mul_f32_e32 v18, 0x4f800000, v17
	v_cmp_gt_f32_e32 vcc, s25, v17
	s_nop 1
	v_cndmask_b32_e32 v17, v17, v18, vcc
	v_sqrt_f32_e32 v18, v17
	s_nop 0
	v_add_u32_e32 v19, -1, v18
	v_fma_f32 v20, -v19, v18, v17
	v_cmp_ge_f32_e64 s[8:9], 0, v20
	v_add_u32_e32 v20, 1, v18
	s_nop 0
	v_cndmask_b32_e64 v19, v18, v19, s[8:9]
	v_fma_f32 v18, -v20, v18, v17
	v_cmp_lt_f32_e64 s[8:9], 0, v18
	s_nop 1
	v_cndmask_b32_e64 v18, v19, v20, s[8:9]
	v_mul_f32_e32 v19, 0x37800000, v18
	v_cndmask_b32_e32 v18, v18, v19, vcc
	v_cmp_class_f32_e32 vcc, v17, v48
	s_nop 1
	v_cndmask_b32_e32 v17, v18, v17, vcc
	v_div_scale_f32 v18, s[8:9], v17, v17, 1.0
	v_rcp_f32_e32 v19, v18
	s_nop 0
	v_fma_f32 v20, -v18, v19, 1.0
	v_fmac_f32_e32 v19, v20, v19
	v_div_scale_f32 v20, vcc, 1.0, v17, 1.0
	v_mul_f32_e32 v21, v20, v19
	v_fma_f32 v22, -v18, v21, v20
	v_fmac_f32_e32 v21, v22, v19
	v_fma_f32 v18, -v18, v21, v20
	v_div_fmas_f32 v18, v18, v19, v21
	v_div_fixup_f32 v18, v18, v17, 1.0
	s_and_saveexec_b64 s[8:9], s[6:7]
	s_cbranch_execz .LBB0_1741
	s_lshl_b64 s[18:19], s[14:15], 3
	s_add_u32 s18, s12, s18
	s_addc_u32 s19, s13, s19
	v_mov_b32_e32 v17, v18
	global_store_dwordx2 v32, v[16:17], s[18:19]
	s_branch .LBB0_1741

.LBB0_1879:
	s_or_b64 exec, exec, s[2:3]
	s_lshl_b64 s[2:3], s[10:11], 11
	v_lshl_add_u64 v[16:17], v[2:3], 0, s[2:3]
	global_load_dwordx2 v[28:29], v[16:17], off nt
	global_load_dwordx2 v[26:27], v[16:17], off offset:512 nt
	global_load_dwordx2 v[24:25], v[16:17], off offset:1024 nt
	global_load_dwordx2 v[20:21], v[16:17], off offset:1536 nt
	s_add_i32 s6, s10, s76
	s_cmp_lt_i32 s6, 0x10100
	s_cselect_b64 s[8:9], -1, 0
	s_and_b64 s[2:3], s[8:9], exec
	s_cselect_b32 s2, s6, s10
	v_mov_b32_e32 v1, v0
	v_mov_b32_e32 v15, v0
	s_ashr_i32 s3, s2, 31
	s_and_saveexec_b64 s[12:13], s[0:1]
	s_cbranch_execz .LBB0_1881
	s_lshl_b64 s[14:15], s[2:3], 7
	v_lshl_add_u64 v[16:17], v[4:5], 0, s[14:15]
	global_load_dwordx2 v[16:17], v[16:17], off
	s_waitcnt vmcnt(0)
	v_mov_b32_e32 v1, v16
	v_mov_b32_e32 v15, v17
.LBB0_1881:
	s_or_b64 exec, exec, s[12:13]
	global_load_dwordx4 v[32:35], v[6:7], off
	global_load_dwordx4 v[36:39], v[8:9], off
	v_mov_b32_e32 v13, v14
	s_lshl_b64 s[2:3], s[2:3], 11
	v_lshl_add_u64 v[42:43], v[2:3], 0, s[2:3]
	v_mov_b32_dpp v13, v13 quad_perm:[1,0,3,2] row_mask:0xf bank_mask:0xf
	v_add_f32_e32 v13, v14, v13
	v_mov_b32_e32 v14, v13
	s_nop 1
	v_mov_b32_dpp v14, v14 quad_perm:[2,3,0,1] row_mask:0xf bank_mask:0xf
	v_add_f32_e32 v13, v13, v14
	v_mov_b32_e32 v14, v13
	s_nop 1
	v_mov_b32_dpp v14, v14 row_ror:4 row_mask:0xf bank_mask:0xf
	v_add_f32_e32 v13, v13, v14
	v_mov_b32_e32 v14, v13
	s_nop 1
	v_mov_b32_dpp v14, v14 row_ror:8 row_mask:0xf bank_mask:0xf
	v_add_f32_e32 v13, v13, v14
	s_nop 0
	v_readfirstlane_b32 s7, v13
	v_mov_b32_e32 v13, v12
	s_nop 1
	v_mov_b32_dpp v13, v13 quad_perm:[1,0,3,2] row_mask:0xf bank_mask:0xf
	v_add_f32_e32 v12, v12, v13
	v_mov_b32_e32 v13, v12
	s_nop 1
	v_mov_b32_dpp v13, v13 quad_perm:[2,3,0,1] row_mask:0xf bank_mask:0xf
	v_add_f32_e32 v12, v12, v13
	v_mov_b32_e32 v13, v12
	s_nop 1
	v_mov_b32_dpp v13, v13 row_ror:4 row_mask:0xf bank_mask:0xf
	v_add_f32_e32 v12, v12, v13
	v_mov_b32_e32 v13, v12
	s_nop 1
	v_mov_b32_dpp v13, v13 row_ror:8 row_mask:0xf bank_mask:0xf
	v_add_f32_e32 v12, v12, v13
	s_nop 0
	v_readfirstlane_b32 s12, v12
	v_cvt_i32_f32_e32 v12, s7
	v_cvt_f32_i32_e32 v13, v12
	v_cvt_i32_f32_e32 v14, s12
	v_cvt_f32_i32_e32 v12, v14
	v_pk_mul_f32 v[40:41], v[12:13], s[4:5] op_sel_hi:[1,0]
	s_nop 0
	v_fma_f32 v12, -v41, v41, v40
	v_max_f32_e32 v12, 0, v12
	v_add_f32_e32 v12, 0x3727c5ac, v12
	v_mul_f32_e32 v13, 0x4f800000, v12
	v_cmp_gt_f32_e32 vcc, s5, v12
	s_nop 1
	v_cndmask_b32_e32 v12, v12, v13, vcc
	v_sqrt_f32_e32 v13, v12
	s_nop 0
	v_add_u32_e32 v14, -1, v13
	v_fma_f32 v16, -v14, v13, v12
	v_cmp_ge_f32_e64 s[2:3], 0, v16
	v_add_u32_e32 v16, 1, v13
	s_nop 0
	v_cndmask_b32_e64 v14, v13, v14, s[2:3]
	v_fma_f32 v13, -v16, v13, v12
	v_cmp_lt_f32_e64 s[2:3], 0, v13
	s_nop 1
	v_cndmask_b32_e64 v13, v14, v16, s[2:3]
	v_mul_f32_e32 v14, 0x37800000, v13
	v_cndmask_b32_e32 v13, v13, v14, vcc
	v_cmp_class_f32_e32 vcc, v12, v30
	s_nop 1
	v_cndmask_b32_e32 v14, v13, v12, vcc
	v_div_scale_f32 v31, s[2:3], v14, v14, 1.0
	v_rcp_f32_e32 v40, v31
	global_load_dwordx2 v[22:23], v[42:43], off nt
	global_load_dwordx2 v[18:19], v[42:43], off offset:512 nt
	global_load_dwordx2 v[16:17], v[42:43], off offset:1024 nt
	global_load_dwordx2 v[12:13], v[42:43], off offset:1536 nt
	s_lshl_b64 s[2:3], s[10:11], 12
	v_fma_f32 v42, -v31, v40, 1.0
	v_fmac_f32_e32 v40, v42, v40
	v_div_scale_f32 v42, vcc, 1.0, v14, 1.0
	v_mul_f32_e32 v43, v42, v40
	v_fma_f32 v44, -v31, v43, v42
	v_fmac_f32_e32 v43, v44, v40
	v_fma_f32 v31, -v31, v43, v42
	v_div_fmas_f32 v31, v31, v40, v43
	v_div_fixup_f32 v14, v31, v14, 1.0
	s_waitcnt vmcnt(9)
	v_lshlrev_b32_e32 v31, 16, v28
	v_and_b32_e32 v40, 0xffff0000, v28
	v_lshlrev_b32_e32 v28, 16, v29
	v_and_b32_e32 v29, 0xffff0000, v29
	v_sub_f32_e32 v29, v29, v41
	v_sub_f32_e32 v28, v28, v41
	v_sub_f32_e32 v43, v40, v41
	v_sub_f32_e32 v42, v31, v41
	v_pk_mul_f32 v[42:43], v[42:43], v[14:15] op_sel_hi:[1,0]
	v_pk_mul_f32 v[28:29], v[28:29], v[14:15] op_sel_hi:[1,0]
	s_waitcnt vmcnt(4)
	v_pk_fma_f32 v[32:33], v[32:33], v[42:43], v[36:37]
	v_pk_fma_f32 v[34:35], v[34:35], v[28:29], v[38:39]
	v_lshl_add_u64 v[42:43], v[10:11], 0, s[2:3]
	global_store_dwordx4 v[42:43], v[32:35], off nt
	global_load_dwordx4 v[32:35], v[6:7], off offset:1024
	s_nop 0
	global_load_dwordx4 v[36:39], v[8:9], off offset:1024
	v_lshlrev_b32_e32 v28, 16, v26
	v_and_b32_e32 v26, 0xffff0000, v26
	v_lshlrev_b32_e32 v31, 16, v27
	v_and_b32_e32 v29, 0xffff0000, v27
	v_sub_f32_e32 v27, v26, v41
	v_sub_f32_e32 v26, v28, v41
	v_sub_f32_e32 v29, v29, v41
	v_sub_f32_e32 v28, v31, v41
	v_pk_mul_f32 v[28:29], v[28:29], v[14:15] op_sel_hi:[1,0]
	v_pk_mul_f32 v[26:27], v[26:27], v[14:15] op_sel_hi:[1,0]
	v_lshlrev_b32_e32 v31, 16, v24
	v_and_b32_e32 v24, 0xffff0000, v24
	s_andn2_b64 vcc, exec, s[8:9]
	s_waitcnt vmcnt(0)
	v_pk_fma_f32 v[26:27], v[32:33], v[26:27], v[36:37]
	v_pk_fma_f32 v[28:29], v[34:35], v[28:29], v[38:39]
	global_store_dwordx4 v[42:43], v[26:29], off offset:1024 nt
	global_load_dwordx4 v[26:29], v[6:7], off offset:2048
	s_nop 0
	global_load_dwordx4 v[32:35], v[8:9], off offset:2048
	v_lshlrev_b32_e32 v36, 16, v25
	v_and_b32_e32 v37, 0xffff0000, v25
	v_sub_f32_e32 v25, v24, v41
	v_sub_f32_e32 v24, v31, v41
	v_sub_f32_e32 v37, v37, v41
	v_sub_f32_e32 v36, v36, v41
	v_pk_mul_f32 v[36:37], v[36:37], v[14:15] op_sel_hi:[1,0]
	v_pk_mul_f32 v[24:25], v[24:25], v[14:15] op_sel_hi:[1,0]
	v_lshlrev_b32_e32 v31, 16, v21
	s_waitcnt vmcnt(0)
	v_pk_fma_f32 v[24:25], v[26:27], v[24:25], v[32:33]
	v_pk_fma_f32 v[26:27], v[28:29], v[36:37], v[34:35]
	global_store_dwordx4 v[42:43], v[24:27], off offset:2048 nt
	global_load_dwordx4 v[24:27], v[6:7], off offset:3072
	s_nop 0
	global_load_dwordx4 v[32:35], v[8:9], off offset:3072
	v_lshlrev_b32_e32 v28, 16, v20
	v_and_b32_e32 v20, 0xffff0000, v20
	v_and_b32_e32 v29, 0xffff0000, v21
	v_sub_f32_e32 v21, v20, v41
	v_sub_f32_e32 v20, v28, v41
	v_sub_f32_e32 v29, v29, v41
	v_sub_f32_e32 v28, v31, v41
	v_pk_mul_f32 v[28:29], v[28:29], v[14:15] op_sel_hi:[1,0]
	v_pk_mul_f32 v[20:21], v[20:21], v[14:15] op_sel_hi:[1,0]
	s_waitcnt vmcnt(0)
	v_pk_fma_f32 v[26:27], v[26:27], v[28:29], v[34:35]
	v_pk_fma_f32 v[24:25], v[24:25], v[20:21], v[32:33]
	global_store_dwordx4 v[42:43], v[24:27], off offset:3072 nt
	s_cbranch_vccnz .LBB0_1876
	global_load_dwordx4 v[24:27], v[6:7], off
	global_load_dwordx4 v[32:35], v[8:9], off
	v_mov_b32_e32 v14, v1
	v_mov_b32_e32 v20, v15
	v_lshlrev_b32_e32 v31, 16, v22
	v_mov_b32_dpp v14, v14 quad_perm:[1,0,3,2] row_mask:0xf bank_mask:0xf
	v_mov_b32_dpp v20, v20 quad_perm:[1,0,3,2] row_mask:0xf bank_mask:0xf
	v_add_f32_e32 v1, v1, v14
	v_add_f32_e32 v14, v15, v20
	v_mov_b32_e32 v15, v1
	v_mov_b32_e32 v20, v14
	v_lshlrev_b32_e32 v21, 16, v23
	v_mov_b32_dpp v15, v15 quad_perm:[2,3,0,1] row_mask:0xf bank_mask:0xf
	v_mov_b32_dpp v20, v20 quad_perm:[2,3,0,1] row_mask:0xf bank_mask:0xf
	v_add_f32_e32 v1, v1, v15
	v_add_f32_e32 v14, v14, v20
	v_mov_b32_e32 v15, v1
	v_mov_b32_e32 v20, v14
	s_ashr_i32 s7, s6, 31
	v_mov_b32_dpp v15, v15 row_ror:4 row_mask:0xf bank_mask:0xf
	v_mov_b32_dpp v20, v20 row_ror:4 row_mask:0xf bank_mask:0xf
	v_add_f32_e32 v1, v1, v15
	v_add_f32_e32 v14, v14, v20
	v_mov_b32_e32 v15, v1
	v_mov_b32_e32 v20, v14
	s_nop 0
	v_mov_b32_dpp v15, v15 row_ror:8 row_mask:0xf bank_mask:0xf
	v_mov_b32_dpp v20, v20 row_ror:8 row_mask:0xf bank_mask:0xf
	v_add_f32_e32 v1, v1, v15
	v_add_f32_e32 v14, v14, v20
	v_readfirstlane_b32 s2, v1
	v_readfirstlane_b32 s3, v14
	v_and_b32_e32 v20, 0xffff0000, v22
	v_cvt_i32_f32_e32 v1, s2
	v_cvt_i32_f32_e32 v14, s3
	s_lshl_b64 s[2:3], s[6:7], 12
	v_lshl_add_u64 v[28:29], v[10:11], 0, s[2:3]
	v_cvt_f32_i32_e32 v15, v1
	v_cvt_f32_i32_e32 v14, v14
	v_and_b32_e32 v1, 0xffff0000, v23
	v_pk_mul_f32 v[36:37], v[14:15], s[4:5] op_sel_hi:[1,0]
	s_nop 0
	v_fma_f32 v14, -v37, v37, v36
	v_max_f32_e32 v14, 0, v14
	v_add_f32_e32 v14, 0x3727c5ac, v14
	v_mul_f32_e32 v15, 0x4f800000, v14
	v_cmp_gt_f32_e32 vcc, s5, v14
	s_nop 1
	v_cndmask_b32_e32 v22, v14, v15, vcc
	v_sqrt_f32_e32 v23, v22
	v_sub_f32_e32 v15, v1, v37
	v_sub_f32_e32 v14, v21, v37
	v_sub_f32_e32 v21, v20, v37
	v_add_u32_e32 v1, -1, v23
	v_add_u32_e32 v20, 1, v23
	v_fma_f32 v36, -v1, v23, v22
	v_fma_f32 v38, -v20, v23, v22
	v_cmp_ge_f32_e64 s[2:3], 0, v36
	s_nop 1
	v_cndmask_b32_e64 v1, v23, v1, s[2:3]
	v_cmp_lt_f32_e64 s[2:3], 0, v38
	s_nop 1
	v_cndmask_b32_e64 v1, v1, v20, s[2:3]
	v_mul_f32_e32 v20, 0x37800000, v1
	v_cndmask_b32_e32 v1, v1, v20, vcc
	v_cmp_class_f32_e32 vcc, v22, v30
	v_sub_f32_e32 v20, v31, v37
	s_nop 0
	v_cndmask_b32_e32 v1, v1, v22, vcc
	v_div_scale_f32 v22, s[2:3], v1, v1, 1.0
	v_rcp_f32_e32 v23, v22
	v_div_scale_f32 v31, vcc, 1.0, v1, 1.0
	v_fma_f32 v36, -v22, v23, 1.0
	v_fmac_f32_e32 v23, v36, v23
	v_mul_f32_e32 v36, v31, v23
	v_fma_f32 v38, -v22, v36, v31
	v_fmac_f32_e32 v36, v38, v23
	v_fma_f32 v22, -v22, v36, v31
	v_div_fmas_f32 v22, v22, v23, v36
	v_div_fixup_f32 v36, v22, v1, 1.0
	v_pk_mul_f32 v[20:21], v[20:21], v[36:37] op_sel_hi:[1,0]
	v_pk_mul_f32 v[14:15], v[14:15], v[36:37] op_sel_hi:[1,0]
	s_waitcnt vmcnt(0)
	v_pk_fma_f32 v[20:21], v[24:25], v[20:21], v[32:33]
	v_pk_fma_f32 v[22:23], v[26:27], v[14:15], v[34:35]
	global_store_dwordx4 v[28:29], v[20:23], off nt
	global_load_dwordx4 v[20:23], v[6:7], off offset:1024
	s_nop 0
	global_load_dwordx4 v[24:27], v[8:9], off offset:1024
	v_lshlrev_b32_e32 v1, 16, v18
	v_and_b32_e32 v14, 0xffff0000, v18
	v_lshlrev_b32_e32 v18, 16, v19
	v_and_b32_e32 v19, 0xffff0000, v19
	v_sub_f32_e32 v15, v14, v37
	v_sub_f32_e32 v14, v1, v37
	v_sub_f32_e32 v19, v19, v37
	v_sub_f32_e32 v18, v18, v37
	v_pk_mul_f32 v[32:33], v[18:19], v[36:37] op_sel_hi:[1,0]
	v_pk_mul_f32 v[14:15], v[14:15], v[36:37] op_sel_hi:[1,0]
	v_lshlrev_b32_e32 v1, 16, v16
	s_waitcnt vmcnt(0)
	v_pk_fma_f32 v[18:19], v[20:21], v[14:15], v[24:25]
	v_pk_fma_f32 v[20:21], v[22:23], v[32:33], v[26:27]
	global_store_dwordx4 v[28:29], v[18:21], off offset:1024 nt
	global_load_dwordx4 v[18:21], v[6:7], off offset:2048
	s_nop 0
	global_load_dwordx4 v[22:25], v[8:9], off offset:2048
	v_and_b32_e32 v14, 0xffff0000, v16
	v_lshlrev_b32_e32 v16, 16, v17
	v_and_b32_e32 v17, 0xffff0000, v17
	v_sub_f32_e32 v15, v14, v37
	v_sub_f32_e32 v14, v1, v37
	v_sub_f32_e32 v17, v17, v37
	v_sub_f32_e32 v16, v16, v37
	v_pk_mul_f32 v[16:17], v[16:17], v[36:37] op_sel_hi:[1,0]
	v_pk_mul_f32 v[14:15], v[14:15], v[36:37] op_sel_hi:[1,0]
	v_lshlrev_b32_e32 v1, 16, v12
	v_and_b32_e32 v12, 0xffff0000, v12
	s_waitcnt vmcnt(0)
	v_pk_fma_f32 v[14:15], v[18:19], v[14:15], v[22:23]
	v_pk_fma_f32 v[16:17], v[20:21], v[16:17], v[24:25]
	global_store_dwordx4 v[28:29], v[14:17], off offset:2048 nt
	global_load_dwordx4 v[14:17], v[6:7], off offset:3072
	s_nop 0
	global_load_dwordx4 v[18:21], v[8:9], off offset:3072
	v_lshlrev_b32_e32 v22, 16, v13
	v_and_b32_e32 v23, 0xffff0000, v13
	v_sub_f32_e32 v13, v12, v37
	v_sub_f32_e32 v12, v1, v37
	v_sub_f32_e32 v23, v23, v37
	v_sub_f32_e32 v22, v22, v37
	v_pk_mul_f32 v[22:23], v[22:23], v[36:37] op_sel_hi:[1,0]
	v_pk_mul_f32 v[12:13], v[12:13], v[36:37] op_sel_hi:[1,0]
	s_waitcnt vmcnt(0)
	v_pk_fma_f32 v[12:13], v[14:15], v[12:13], v[18:19]
	v_pk_fma_f32 v[14:15], v[16:17], v[22:23], v[20:21]
	global_store_dwordx4 v[28:29], v[12:15], off offset:3072 nt
	s_branch .LBB0_1876
